# attention S=QK^T stage: K-fragment LDS reads issued two key blocks ahead with counted waits (was read/wait/MFMA per fragment)
# baseline (speedup 1.0000x reference)
; #define LAS __attribute__((address_space(3)))
; __device__ __forceinline__ void attn_phase(const Params& p, LAS unsigned char* lds) {
;     ...
;         f32x4 sa[16];
; #pragma unroll
;         for (int kb = 0; kb < 16; ++kb) {
;             sa[kb] = (f32x4){0.f, 0.f, 0.f, 0.f};
; #pragma unroll
;             for (int ks = 0; ks < 4; ++ks) {
;                 const bf16x8 Kf = *(const LAS bf16x8*)(KL + (kb * 16 + fr) * 136 + ks * 32 + fq * 8);
;                 sa[kb] = __builtin_amdgcn_mfma_f32_16x16x32_bf16(Qf[ks], Kf, sa[kb], 0, 0, 0);
;             }
;         }
.LBB0_210:
	s_or_b64 exec, exec, s[86:87]
	s_waitcnt lgkmcnt(0)
	s_barrier
	ds_read_b128 v[148:151], v139
	ds_read_b128 v[152:155], v139 offset:64
	ds_read_b128 v[156:159], v139 offset:128
	ds_read_b128 v[160:163], v139 offset:192
	ds_read_b128 v[176:179], v139 offset:4352
	ds_read_b128 v[180:183], v139 offset:4416
	ds_read_b128 v[184:187], v139 offset:4480
	ds_read_b128 v[188:191], v139 offset:4544
	s_cmp_lg_u32 s33, 0
	v_readlane_b32 s78, v239, 40
	s_cselect_b64 s[40:41], -1, 0
	v_readlane_b32 s79, v239, 41
	s_and_b64 vcc, s[40:41], s[78:79]
	v_readlane_b32 s78, v239, 44
	v_readlane_b32 s79, v239, 45
	s_mov_b32 s33, 0xff61b1e6
	s_ashr_i32 s77, s76, 31
	s_lshl_b64 s[76:77], s[76:77], 14
	s_lshl_b32 s2, s2, 1
	s_waitcnt lgkmcnt(7)
	v_mfma_f32_16x16x32_bf16 v[104:107], v[96:99], v[148:151], 0
	s_waitcnt lgkmcnt(6)
	v_mfma_f32_16x16x32_bf16 v[104:107], v[92:95], v[152:155], v[104:107]
	s_waitcnt lgkmcnt(5)
	v_mfma_f32_16x16x32_bf16 v[104:107], v[88:91], v[156:159], v[104:107]
	s_waitcnt lgkmcnt(4)
	v_mfma_f32_16x16x32_bf16 v[104:107], v[32:35], v[160:163], v[104:107]
	ds_read_b128 v[148:151], v139 offset:8704
	ds_read_b128 v[152:155], v139 offset:8768
	ds_read_b128 v[156:159], v139 offset:8832
	ds_read_b128 v[160:163], v139 offset:8896
	s_waitcnt lgkmcnt(7)
	v_mfma_f32_16x16x32_bf16 v[100:103], v[96:99], v[176:179], 0
	s_waitcnt lgkmcnt(6)
	v_mfma_f32_16x16x32_bf16 v[100:103], v[92:95], v[180:183], v[100:103]
	s_waitcnt lgkmcnt(5)
	v_mfma_f32_16x16x32_bf16 v[100:103], v[88:91], v[184:187], v[100:103]
	s_waitcnt lgkmcnt(4)
	v_mfma_f32_16x16x32_bf16 v[100:103], v[32:35], v[188:191], v[100:103]
	ds_read_b128 v[176:179], v139 offset:13056
	ds_read_b128 v[180:183], v139 offset:13120
	ds_read_b128 v[184:187], v139 offset:13184
	ds_read_b128 v[188:191], v139 offset:13248
	s_waitcnt lgkmcnt(7)
	v_mfma_f32_16x16x32_bf16 v[84:87], v[96:99], v[148:151], 0
	s_waitcnt lgkmcnt(6)
	v_mfma_f32_16x16x32_bf16 v[84:87], v[92:95], v[152:155], v[84:87]
	s_waitcnt lgkmcnt(5)
	v_mfma_f32_16x16x32_bf16 v[84:87], v[88:91], v[156:159], v[84:87]
	s_waitcnt lgkmcnt(4)
	v_mfma_f32_16x16x32_bf16 v[84:87], v[32:35], v[160:163], v[84:87]
	ds_read_b128 v[148:151], v139 offset:17408
	ds_read_b128 v[152:155], v139 offset:17472
	ds_read_b128 v[156:159], v139 offset:17536
	ds_read_b128 v[160:163], v139 offset:17600
	s_waitcnt lgkmcnt(7)
	v_mfma_f32_16x16x32_bf16 v[80:83], v[96:99], v[176:179], 0
	s_waitcnt lgkmcnt(6)
	v_mfma_f32_16x16x32_bf16 v[80:83], v[92:95], v[180:183], v[80:83]
	s_waitcnt lgkmcnt(5)
	v_mfma_f32_16x16x32_bf16 v[80:83], v[88:91], v[184:187], v[80:83]
	s_waitcnt lgkmcnt(4)
	v_mfma_f32_16x16x32_bf16 v[80:83], v[32:35], v[188:191], v[80:83]
	ds_read_b128 v[176:179], v139 offset:21760
	ds_read_b128 v[180:183], v139 offset:21824
	ds_read_b128 v[184:187], v139 offset:21888
	ds_read_b128 v[188:191], v139 offset:21952
	s_waitcnt lgkmcnt(7)
	v_mfma_f32_16x16x32_bf16 v[76:79], v[96:99], v[148:151], 0
	s_waitcnt lgkmcnt(6)
	v_mfma_f32_16x16x32_bf16 v[76:79], v[92:95], v[152:155], v[76:79]
	s_waitcnt lgkmcnt(5)
	v_mfma_f32_16x16x32_bf16 v[76:79], v[88:91], v[156:159], v[76:79]
	s_waitcnt lgkmcnt(4)
	v_mfma_f32_16x16x32_bf16 v[76:79], v[32:35], v[160:163], v[76:79]
	ds_read_b128 v[148:151], v139 offset:26112
	ds_read_b128 v[152:155], v139 offset:26176
	ds_read_b128 v[156:159], v139 offset:26240
	ds_read_b128 v[160:163], v139 offset:26304
	s_waitcnt lgkmcnt(7)
	v_mfma_f32_16x16x32_bf16 v[72:75], v[96:99], v[176:179], 0
	s_waitcnt lgkmcnt(6)
	v_mfma_f32_16x16x32_bf16 v[72:75], v[92:95], v[180:183], v[72:75]
	s_waitcnt lgkmcnt(5)
	v_mfma_f32_16x16x32_bf16 v[72:75], v[88:91], v[184:187], v[72:75]
	s_waitcnt lgkmcnt(4)
	v_mfma_f32_16x16x32_bf16 v[72:75], v[32:35], v[188:191], v[72:75]
	ds_read_b128 v[176:179], v139 offset:30464
	ds_read_b128 v[180:183], v139 offset:30528
	ds_read_b128 v[184:187], v139 offset:30592
	ds_read_b128 v[188:191], v139 offset:30656
	s_waitcnt lgkmcnt(7)
	v_mfma_f32_16x16x32_bf16 v[68:71], v[96:99], v[148:151], 0
	s_waitcnt lgkmcnt(6)
	v_mfma_f32_16x16x32_bf16 v[68:71], v[92:95], v[152:155], v[68:71]
	s_waitcnt lgkmcnt(5)
	v_mfma_f32_16x16x32_bf16 v[68:71], v[88:91], v[156:159], v[68:71]
	s_waitcnt lgkmcnt(4)
	v_mfma_f32_16x16x32_bf16 v[68:71], v[32:35], v[160:163], v[68:71]
	ds_read_b128 v[148:151], v139 offset:34816
	ds_read_b128 v[152:155], v139 offset:34880
	ds_read_b128 v[156:159], v139 offset:34944
	ds_read_b128 v[160:163], v139 offset:35008
	s_waitcnt lgkmcnt(7)
	v_mfma_f32_16x16x32_bf16 v[64:67], v[96:99], v[176:179], 0
	s_waitcnt lgkmcnt(6)
	v_mfma_f32_16x16x32_bf16 v[64:67], v[92:95], v[180:183], v[64:67]
	s_waitcnt lgkmcnt(5)
	v_mfma_f32_16x16x32_bf16 v[64:67], v[88:91], v[184:187], v[64:67]
	s_waitcnt lgkmcnt(4)
	v_mfma_f32_16x16x32_bf16 v[64:67], v[32:35], v[188:191], v[64:67]
	ds_read_b128 v[176:179], v139 offset:39168
	ds_read_b128 v[180:183], v139 offset:39232
	ds_read_b128 v[184:187], v139 offset:39296
	ds_read_b128 v[188:191], v139 offset:39360
	s_waitcnt lgkmcnt(7)
	v_mfma_f32_16x16x32_bf16 v[60:63], v[96:99], v[148:151], 0
	s_waitcnt lgkmcnt(6)
	v_mfma_f32_16x16x32_bf16 v[60:63], v[92:95], v[152:155], v[60:63]
	s_waitcnt lgkmcnt(5)
	v_mfma_f32_16x16x32_bf16 v[60:63], v[88:91], v[156:159], v[60:63]
	s_waitcnt lgkmcnt(4)
	v_mfma_f32_16x16x32_bf16 v[60:63], v[32:35], v[160:163], v[60:63]
	ds_read_b128 v[148:151], v139 offset:43520
	ds_read_b128 v[152:155], v139 offset:43584
	ds_read_b128 v[156:159], v139 offset:43648
	ds_read_b128 v[160:163], v139 offset:43712
	s_waitcnt lgkmcnt(7)
	v_mfma_f32_16x16x32_bf16 v[56:59], v[96:99], v[176:179], 0
	s_waitcnt lgkmcnt(6)
	v_mfma_f32_16x16x32_bf16 v[56:59], v[92:95], v[180:183], v[56:59]
	s_waitcnt lgkmcnt(5)
; #define LAS __attribute__((address_space(3)))
; __device__ __forceinline__ void attn_phase(const Params& p, LAS unsigned char* lds) {
;     ...
;         f32x4 sa[16];
; #pragma unroll
;         for (int kb = 0; kb < 16; ++kb) {
;             sa[kb] = (f32x4){0.f, 0.f, 0.f, 0.f};
; #pragma unroll
;             for (int ks = 0; ks < 4; ++ks) {
;                 const bf16x8 Kf = *(const LAS bf16x8*)(KL + (kb * 16 + fr) * 136 + ks * 32 + fq * 8);
;                 sa[kb] = __builtin_amdgcn_mfma_f32_16x16x32_bf16(Qf[ks], Kf, sa[kb], 0, 0, 0);
;             }
;         }
;         float mx[4] = {-3.0e38f, -3.0e38f, -3.0e38f, -3.0e38f};
; #pragma unroll
;         for (int kb = 0; kb < 16; ++kb)
; #pragma unroll
;             for (int j = 0; j < 4; ++j) {
;                 const int diff = (wid * 16 + fq * 4 + j) + 128 - kb * 16 - fr;
;                 const int kk = i0 - 128 + kb * 16 + fr;
;                 const bool valid = (kk >= 0) && (diff >= 0) && (diff <= 128);
;                 const float s = valid ? sa[kb][j] * scale : -1.0e30f;
;                 sa[kb][j] = s; mx[j] = fmaxf(mx[j], s);
;             }
	v_mfma_f32_16x16x32_bf16 v[56:59], v[88:91], v[184:187], v[56:59]
	s_waitcnt lgkmcnt(4)
	v_mfma_f32_16x16x32_bf16 v[56:59], v[32:35], v[188:191], v[56:59]
	ds_read_b128 v[176:179], v139 offset:47872
	ds_read_b128 v[180:183], v139 offset:47936
	ds_read_b128 v[184:187], v139 offset:48000
	ds_read_b128 v[188:191], v139 offset:48064
	s_waitcnt lgkmcnt(7)
	v_mfma_f32_16x16x32_bf16 v[52:55], v[96:99], v[148:151], 0
	s_waitcnt lgkmcnt(6)
	v_mfma_f32_16x16x32_bf16 v[52:55], v[92:95], v[152:155], v[52:55]
	s_waitcnt lgkmcnt(5)
	v_mfma_f32_16x16x32_bf16 v[52:55], v[88:91], v[156:159], v[52:55]
	s_waitcnt lgkmcnt(4)
	v_mfma_f32_16x16x32_bf16 v[52:55], v[32:35], v[160:163], v[52:55]
	ds_read_b128 v[148:151], v139 offset:52224
	ds_read_b128 v[152:155], v139 offset:52288
	ds_read_b128 v[156:159], v139 offset:52352
	ds_read_b128 v[160:163], v139 offset:52416
	s_waitcnt lgkmcnt(7)
	v_mfma_f32_16x16x32_bf16 v[48:51], v[96:99], v[176:179], 0
	s_waitcnt lgkmcnt(6)
	v_mfma_f32_16x16x32_bf16 v[48:51], v[92:95], v[180:183], v[48:51]
	s_waitcnt lgkmcnt(5)
	v_mfma_f32_16x16x32_bf16 v[48:51], v[88:91], v[184:187], v[48:51]
	s_waitcnt lgkmcnt(4)
	v_mfma_f32_16x16x32_bf16 v[48:51], v[32:35], v[188:191], v[48:51]
	ds_read_b128 v[176:179], v139 offset:56576
	ds_read_b128 v[180:183], v139 offset:56640
	ds_read_b128 v[184:187], v139 offset:56704
	ds_read_b128 v[188:191], v139 offset:56768
	s_waitcnt lgkmcnt(7)
	v_mfma_f32_16x16x32_bf16 v[44:47], v[96:99], v[148:151], 0
	s_waitcnt lgkmcnt(6)
	v_mfma_f32_16x16x32_bf16 v[44:47], v[92:95], v[152:155], v[44:47]
	s_waitcnt lgkmcnt(5)
	v_mfma_f32_16x16x32_bf16 v[44:47], v[88:91], v[156:159], v[44:47]
	s_waitcnt lgkmcnt(4)
	v_mfma_f32_16x16x32_bf16 v[44:47], v[32:35], v[160:163], v[44:47]
	ds_read_b128 v[148:151], v139 offset:60928
	ds_read_b128 v[152:155], v139 offset:60992
	ds_read_b128 v[156:159], v139 offset:61056
	ds_read_b128 v[160:163], v139 offset:61120
	s_waitcnt lgkmcnt(7)
	v_mfma_f32_16x16x32_bf16 v[40:43], v[96:99], v[176:179], 0
	s_waitcnt lgkmcnt(6)
	v_mfma_f32_16x16x32_bf16 v[40:43], v[92:95], v[180:183], v[40:43]
	s_waitcnt lgkmcnt(5)
	v_mfma_f32_16x16x32_bf16 v[40:43], v[88:91], v[184:187], v[40:43]
	s_waitcnt lgkmcnt(4)
	v_mfma_f32_16x16x32_bf16 v[40:43], v[32:35], v[188:191], v[40:43]
	ds_read_b128 v[176:179], v139 offset:65280
	ds_read_b128 v[180:183], v139 offset:65344
	ds_read_b128 v[184:187], v139 offset:65408
	ds_read_b128 v[188:191], v139 offset:65472
	s_waitcnt lgkmcnt(7)
	v_mfma_f32_16x16x32_bf16 v[36:39], v[96:99], v[148:151], 0
	s_waitcnt lgkmcnt(6)
	v_mfma_f32_16x16x32_bf16 v[36:39], v[92:95], v[152:155], v[36:39]
	s_waitcnt lgkmcnt(5)
	v_mfma_f32_16x16x32_bf16 v[36:39], v[88:91], v[156:159], v[36:39]
	s_waitcnt lgkmcnt(4)
	v_mfma_f32_16x16x32_bf16 v[36:39], v[32:35], v[160:163], v[36:39]
	s_waitcnt lgkmcnt(3)
	v_mfma_f32_16x16x32_bf16 v[96:99], v[96:99], v[176:179], 0
	s_waitcnt lgkmcnt(2)
	v_mfma_f32_16x16x32_bf16 v[92:95], v[92:95], v[180:183], v[96:99]
	s_waitcnt lgkmcnt(1)
	v_mfma_f32_16x16x32_bf16 v[88:91], v[88:91], v[184:187], v[92:95]
	s_waitcnt lgkmcnt(0)
	v_mfma_f32_16x16x32_bf16 v[32:35], v[32:35], v[188:191], v[88:91]
	v_mul_f32_e32 v84, 0x3db504f3, v84
	v_mul_f32_e32 v85, 0x3db504f3, v85
	v_mul_f32_e32 v86, 0x3db504f3, v86
	v_mul_f32_e32 v87, 0x3db504f3, v87
	v_mul_f32_e32 v80, 0x3db504f3, v80
	v_mul_f32_e32 v81, 0x3db504f3, v81
	v_mul_f32_e32 v82, 0x3db504f3, v82
	v_mul_f32_e32 v83, 0x3db504f3, v83
	v_mul_f32_e32 v76, 0x3db504f3, v76
	v_mul_f32_e32 v77, 0x3db504f3, v77
	v_mul_f32_e32 v78, 0x3db504f3, v78
	v_mul_f32_e32 v79, 0x3db504f3, v79
	v_mul_f32_e32 v72, 0x3db504f3, v72
	v_mul_f32_e32 v73, 0x3db504f3, v73
	v_mul_f32_e32 v74, 0x3db504f3, v74
	v_mul_f32_e32 v75, 0x3db504f3, v75
	v_mul_f32_e32 v68, 0x3db504f3, v68
	v_mul_f32_e32 v69, 0x3db504f3, v69
	v_mul_f32_e32 v70, 0x3db504f3, v70
	v_mul_f32_e32 v71, 0x3db504f3, v71
	v_mul_f32_e32 v64, 0x3db504f3, v64
	v_mul_f32_e32 v65, 0x3db504f3, v65
	v_mul_f32_e32 v66, 0x3db504f3, v66
	v_mul_f32_e32 v67, 0x3db504f3, v67
	v_mul_f32_e32 v60, 0x3db504f3, v60
	v_mul_f32_e32 v56, 0x3db504f3, v56
	v_mul_f32_e32 v57, 0x3db504f3, v57
	v_mul_f32_e32 v52, 0x3db504f3, v52
	v_mul_f32_e32 v48, 0x3db504f3, v48
	v_mul_f32_e32 v49, 0x3db504f3, v49
	v_mul_f32_e32 v44, 0x3db504f3, v44
	v_mul_f32_e32 v40, 0x3db504f3, v40
	v_mul_f32_e32 v41, 0x3db504f3, v41
	v_mul_f32_e32 v36, 0x3db504f3, v36
	v_mul_f32_e32 v93, 0x3db504f3, v102
	s_nop 1
	v_mul_f32_e32 v88, 0x3db504f3, v104
	v_cndmask_b32_e32 v90, v204, v88, vcc
	s_and_b64 vcc, s[40:41], s[78:79]
	v_readlane_b32 s78, v239, 46
	v_mul_f32_e32 v88, 0x3db504f3, v105
	v_readlane_b32 s79, v239, 47
	v_cndmask_b32_e32 v91, v204, v88, vcc
	s_and_b64 vcc, s[40:41], s[78:79]
	v_readlane_b32 s78, v239, 48
	v_mul_f32_e32 v88, 0x3db504f3, v106
	v_readlane_b32 s79, v239, 49
	v_cndmask_b32_e32 v92, v204, v88, vcc
	s_and_b64 vcc, s[40:41], s[78:79]
	v_readlane_b32 s78, v239, 50
	v_mul_f32_e32 v88, 0x3db504f3, v107
	v_readlane_b32 s79, v239, 51
	v_cndmask_b32_e32 v94, v204, v88, vcc
	s_and_b64 vcc, s[40:41], s[78:79]
	v_readlane_b32 s78, v239, 52
	v_mul_f32_e32 v88, 0x3db504f3, v100
	v_readlane_b32 s79, v239, 53
	v_cndmask_b32_e32 v88, v204, v88, vcc
	s_and_b64 vcc, s[40:41], s[78:79]
	v_readlane_b32 s78, v239, 54
	v_mul_f32_e32 v89, 0x3db504f3, v101
	v_readlane_b32 s79, v239, 55
	v_cndmask_b32_e32 v89, v204, v89, vcc
	s_and_b64 vcc, s[40:41], s[78:79]
	v_readlane_b32 s78, v239, 56
	v_readlane_b32 s79, v239, 57
	v_cndmask_b32_e32 v93, v204, v93, vcc
	s_and_b64 vcc, s[40:41], s[78:79]
	v_readlane_b32 s78, v239, 58
	v_mul_f32_e32 v95, 0x3db504f3, v103
	v_readlane_b32 s79, v239, 59
	v_cndmask_b32_e32 v95, v204, v95, vcc
; __device__ __forceinline__ void attn_phase(const Params& p, LAS unsigned char* lds) {
;     ...
;         float mx[4] = {-3.0e38f, -3.0e38f, -3.0e38f, -3.0e38f};
; #pragma unroll
;         for (int kb = 0; kb < 16; ++kb)
; #pragma unroll
;             for (int j = 0; j < 4; ++j) {
;                 const int diff = (wid * 16 + fq * 4 + j) + 128 - kb * 16 - fr;
;                 const int kk = i0 - 128 + kb * 16 + fr;
;                 const bool valid = (kk >= 0) && (diff >= 0) && (diff <= 128);
;                 const float s = valid ? sa[kb][j] * scale : -1.0e30f;
;                 sa[kb][j] = s; mx[j] = fmaxf(mx[j], s);
;             }
; #pragma unroll
;         for (int j = 0; j < 4; ++j) {
; #pragma unroll
;             for (int o = 1; o < 16; o <<= 1) mx[j] = fmaxf(mx[j], __shfl_xor(mx[j], o));
	s_and_b64 vcc, s[40:41], s[78:79]
	v_readlane_b32 s78, v239, 60
	v_readlane_b32 s79, v239, 61
	v_cndmask_b32_e32 v84, v204, v84, vcc
	s_and_b64 vcc, s[40:41], s[78:79]
	v_readlane_b32 s78, v239, 62
	v_readlane_b32 s79, v239, 63
	v_cndmask_b32_e32 v85, v204, v85, vcc
	s_and_b64 vcc, s[40:41], s[78:79]
	v_readlane_b32 s78, v238, 0
	v_readlane_b32 s79, v238, 1
	v_cndmask_b32_e32 v86, v204, v86, vcc
	s_and_b64 vcc, s[40:41], s[78:79]
	v_readlane_b32 s78, v238, 2
	v_readlane_b32 s79, v238, 3
	v_cndmask_b32_e32 v87, v204, v87, vcc
	s_and_b64 vcc, s[40:41], s[78:79]
	v_readlane_b32 s78, v238, 4
	v_readlane_b32 s79, v238, 5
	v_cndmask_b32_e32 v80, v204, v80, vcc
	s_and_b64 vcc, s[40:41], s[78:79]
	v_readlane_b32 s78, v238, 6
	v_readlane_b32 s79, v238, 7
	v_cndmask_b32_e32 v81, v204, v81, vcc
	s_and_b64 vcc, s[40:41], s[78:79]
	v_readlane_b32 s78, v238, 8
	v_readlane_b32 s79, v238, 9
	v_cndmask_b32_e32 v82, v204, v82, vcc
	s_and_b64 vcc, s[40:41], s[78:79]
	v_readlane_b32 s78, v238, 10
	v_readlane_b32 s79, v238, 11
	v_cndmask_b32_e32 v83, v204, v83, vcc
	s_and_b64 vcc, s[40:41], s[78:79]
	v_readlane_b32 s78, v238, 12
	v_readlane_b32 s79, v238, 13
	v_cndmask_b32_e32 v76, v204, v76, vcc
	s_and_b64 vcc, s[40:41], s[78:79]
	v_readlane_b32 s78, v238, 14
	v_readlane_b32 s79, v238, 15
	v_cndmask_b32_e32 v77, v204, v77, vcc
	s_and_b64 vcc, s[40:41], s[78:79]
	v_readlane_b32 s78, v238, 16
	v_readlane_b32 s79, v238, 17
	v_cndmask_b32_e32 v78, v204, v78, vcc
	s_and_b64 vcc, s[40:41], s[78:79]
	v_readlane_b32 s78, v238, 18
	v_readlane_b32 s79, v238, 19
	v_cndmask_b32_e32 v79, v204, v79, vcc
	s_and_b64 vcc, s[40:41], s[78:79]
	v_readlane_b32 s78, v238, 20
	v_readlane_b32 s79, v238, 21
	v_cndmask_b32_e32 v72, v204, v72, vcc
	s_and_b64 vcc, s[40:41], s[78:79]
	v_readlane_b32 s78, v238, 22
	v_readlane_b32 s79, v238, 23
	v_cndmask_b32_e32 v73, v204, v73, vcc
	s_and_b64 vcc, s[40:41], s[78:79]
	v_readlane_b32 s78, v238, 24
	v_readlane_b32 s79, v238, 25
	v_cndmask_b32_e32 v74, v204, v74, vcc
	s_and_b64 vcc, s[40:41], s[78:79]
	v_readlane_b32 s78, v238, 26
	v_readlane_b32 s79, v238, 27
	v_cndmask_b32_e32 v75, v204, v75, vcc
	s_and_b64 vcc, s[40:41], s[78:79]
	v_readlane_b32 s78, v238, 28
	v_readlane_b32 s79, v238, 29
	v_cndmask_b32_e32 v68, v204, v68, vcc
	s_and_b64 vcc, s[40:41], s[78:79]
	v_readlane_b32 s78, v238, 30
	v_readlane_b32 s79, v238, 31
	v_cndmask_b32_e32 v69, v204, v69, vcc
	s_and_b64 vcc, s[40:41], s[78:79]
	v_readlane_b32 s78, v238, 32
	v_readlane_b32 s79, v238, 33
	v_cndmask_b32_e32 v70, v204, v70, vcc
	s_and_b64 vcc, s[40:41], s[78:79]
	v_readlane_b32 s78, v238, 34
	v_readlane_b32 s79, v238, 35
	v_cndmask_b32_e32 v71, v204, v71, vcc
	s_and_b64 vcc, s[40:41], s[78:79]
	v_readlane_b32 s78, v238, 36
	v_readlane_b32 s79, v238, 37
	v_cndmask_b32_e32 v64, v204, v64, vcc
	s_and_b64 vcc, s[40:41], s[78:79]
	v_readlane_b32 s78, v238, 38
	v_readlane_b32 s79, v238, 39
	v_cndmask_b32_e32 v65, v204, v65, vcc
	s_and_b64 vcc, s[40:41], s[78:79]
	v_readlane_b32 s78, v238, 40
	v_readlane_b32 s79, v238, 41
	v_cndmask_b32_e32 v66, v204, v66, vcc
	s_and_b64 vcc, s[40:41], s[78:79]
	v_readlane_b32 s40, v238, 42
	v_max3_f32 v96, v90, s33, v88
	v_max3_f32 v97, v91, s33, v89
	v_readlane_b32 s41, v238, 43
	v_max3_f32 v96, v96, v84, v80
	v_max3_f32 v97, v97, v85, v81
	v_cndmask_b32_e64 v101, v204, v60, s[40:41]
	v_readlane_b32 s40, v238, 44
	v_max3_f32 v99, v94, s33, v95
	v_max3_f32 v96, v96, v76, v72
	v_max3_f32 v97, v97, v77, v73
	v_mul_f32_e32 v60, 0x3db504f3, v61
	v_readlane_b32 s41, v238, 45
	v_max3_f32 v99, v99, v87, v83
	v_max3_f32 v96, v96, v68, v64
	v_max3_f32 v102, v97, v69, v65
	v_cndmask_b32_e64 v100, v204, v60, s[40:41]
	v_readlane_b32 s40, v238, 46
	v_cndmask_b32_e64 v97, v204, v56, s[52:53]
	v_max3_f32 v98, v92, s33, v93
	v_max3_f32 v99, v99, v79, v75
	v_cndmask_b32_e32 v67, v204, v67, vcc
	v_mul_f32_e32 v60, 0x3db504f3, v62
	v_readlane_b32 s41, v238, 47
	v_max3_f32 v56, v96, v101, v97
	v_cndmask_b32_e64 v96, v204, v57, s[54:55]
	v_mul_f32_e32 v57, 0x3db504f3, v58
	v_max3_f32 v98, v98, v86, v82
	v_max3_f32 v104, v99, v71, v67
	v_cndmask_b32_e64 v99, v204, v60, s[40:41]
	v_mul_f32_e32 v60, 0x3db504f3, v63
	v_cndmask_b32_e64 v63, v204, v57, s[56:57]
	v_mul_f32_e32 v57, 0x3db504f3, v59
	v_max3_f32 v98, v98, v78, v74
	v_cndmask_b32_e64 v62, v204, v57, s[58:59]
	v_cndmask_b32_e64 v61, v204, v52, s[60:61]
	v_mul_f32_e32 v52, 0x3db504f3, v53
	v_cndmask_b32_e64 v57, v204, v48, s[68:69]
	v_max3_f32 v103, v98, v70, v66
	v_cndmask_b32_e64 v98, v204, v60, s[48:49]
	v_cndmask_b32_e64 v60, v204, v52, s[62:63]
	v_mul_f32_e32 v52, 0x3db504f3, v54
	v_max3_f32 v48, v56, v61, v57
	v_cndmask_b32_e64 v56, v204, v49, s[70:71]
	v_mul_f32_e32 v49, 0x3db504f3, v50
	v_cndmask_b32_e64 v59, v204, v52, s[64:65]
	v_mul_f32_e32 v52, 0x3db504f3, v55
	v_cndmask_b32_e64 v55, v204, v49, s[42:43]
	v_mul_f32_e32 v49, 0x3db504f3, v51
	v_cndmask_b32_e64 v53, v204, v44, s[0:1]
	v_mul_f32_e32 v44, 0x3db504f3, v45
	v_cndmask_b32_e64 v58, v204, v52, s[66:67]
	v_cndmask_b32_e64 v54, v204, v49, s[6:7]
	v_cndmask_b32_e64 v52, v204, v44, s[8:9]
	v_mul_f32_e32 v44, 0x3db504f3, v46
	v_cndmask_b32_e64 v49, v204, v40, s[14:15]
	v_cndmask_b32_e64 v51, v204, v44, s[10:11]
	v_mul_f32_e32 v44, 0x3db504f3, v47
	v_max3_f32 v40, v48, v53, v49
	v_cndmask_b32_e64 v48, v204, v41, s[16:17]
	v_mul_f32_e32 v41, 0x3db504f3, v42
	v_cndmask_b32_e64 v45, v204, v36, s[22:23]
	v_mul_f32_e32 v36, 0x3db504f3, v37
	v_cndmask_b32_e64 v50, v204, v44, s[12:13]
	v_cndmask_b32_e64 v47, v204, v41, s[18:19]
	v_mul_f32_e32 v41, 0x3db504f3, v43
	v_cndmask_b32_e64 v44, v204, v36, s[24:25]
	v_mul_f32_e32 v36, 0x3db504f3, v38
	v_mul_f32_e32 v32, 0x3db504f3, v32
	v_cndmask_b32_e64 v46, v204, v41, s[20:21]
	v_cndmask_b32_e64 v43, v204, v36, s[26:27]
	v_mul_f32_e32 v36, 0x3db504f3, v39
	v_cndmask_b32_e64 v41, v204, v32, s[30:31]
	v_cndmask_b32_e64 v42, v204, v36, s[28:29]
	v_max3_f32 v36, v40, v45, v41
	ds_bpermute_b32 v38, v126, v36
	v_max3_f32 v102, v102, v100, v96
	v_max3_f32 v102, v102, v60, v56
	v_mul_f32_e32 v32, 0x3db504f3, v33
	v_max3_f32 v102, v102, v52, v48
	s_waitcnt lgkmcnt(0)
; __device__ __forceinline__ bf16_t f2bf(float f) { return (bf16_t)(cvt_pk_bf16(f, 0.f) & 0xffffu); }
; __device__ __forceinline__ void attn_phase(const Params& p, LAS unsigned char* lds) {
;     ...
; #pragma unroll
;         for (int j = 0; j < 4; ++j) {
; #pragma unroll
;             for (int o = 1; o < 16; o <<= 1) mx[j] = fmaxf(mx[j], __shfl_xor(mx[j], o));
;         }
;         float ls[4] = {0.f, 0.f, 0.f, 0.f};
; #pragma unroll
;         for (int kb = 0; kb < 16; ++kb)
; #pragma unroll
;             for (int j = 0; j < 4; ++j) {
;                 const float pv = __expf(sa[kb][j] - mx[j]);
;                 ls[j] += pv;
;                 PLw[(fq * 4 + j) * 264 + kb * 16 + fr] = f2bf(pv);
;             }
	v_max_f32_e32 v38, v38, v38
	v_max_f32_e32 v36, v36, v38
	ds_bpermute_b32 v38, v127, v36
	v_cndmask_b32_e64 v40, v204, v32, s[34:35]
	v_max3_f32 v37, v102, v44, v40
	v_max3_f32 v103, v103, v99, v63
	v_max3_f32 v103, v103, v59, v55
	s_waitcnt lgkmcnt(0)
	v_max_f32_e32 v38, v38, v38
	v_max_f32_e32 v36, v36, v38
	ds_bpermute_b32 v38, v128, v36
	v_mul_f32_e32 v32, 0x3db504f3, v34
	v_max3_f32 v103, v103, v51, v47
	v_cndmask_b32_e64 v33, v204, v32, s[36:37]
	v_max3_f32 v34, v103, v43, v33
	s_waitcnt lgkmcnt(0)
	v_max_f32_e32 v38, v38, v38
	v_max_f32_e32 v36, v36, v38
	ds_bpermute_b32 v38, v129, v36
	v_max3_f32 v104, v104, v98, v62
	v_max3_f32 v104, v104, v58, v54
	v_mul_f32_e32 v32, 0x3db504f3, v35
	v_max3_f32 v104, v104, v50, v46
	s_waitcnt lgkmcnt(0)
	v_max_f32_e32 v38, v38, v38
	v_max_f32_e32 v39, v36, v38
	ds_bpermute_b32 v36, v126, v37
	v_cndmask_b32_e64 v32, v204, v32, s[38:39]
	v_max3_f32 v35, v104, v42, v32
	s_waitcnt lgkmcnt(0)
	v_max_f32_e32 v36, v36, v36
	v_max_f32_e32 v36, v37, v36
	ds_bpermute_b32 v37, v127, v36
	s_waitcnt lgkmcnt(0)
	v_max_f32_e32 v37, v37, v37
	v_max_f32_e32 v36, v36, v37
	ds_bpermute_b32 v37, v128, v36
	s_waitcnt lgkmcnt(0)
	v_max_f32_e32 v37, v37, v37
	v_max_f32_e32 v36, v36, v37
	ds_bpermute_b32 v37, v129, v36
	s_waitcnt lgkmcnt(0)
	v_max_f32_e32 v37, v37, v37
	v_max_f32_e32 v38, v36, v37
	ds_bpermute_b32 v36, v126, v34
	s_waitcnt lgkmcnt(0)
	v_max_f32_e32 v36, v36, v36
	v_max_f32_e32 v34, v34, v36
	ds_bpermute_b32 v36, v127, v34
	s_waitcnt lgkmcnt(0)
	v_max_f32_e32 v36, v36, v36
	v_max_f32_e32 v34, v34, v36
	ds_bpermute_b32 v36, v128, v34
	s_waitcnt lgkmcnt(0)
	v_max_f32_e32 v36, v36, v36
	v_max_f32_e32 v34, v34, v36
	ds_bpermute_b32 v36, v129, v34
	s_waitcnt lgkmcnt(0)
	v_max_f32_e32 v36, v36, v36
	v_max_f32_e32 v37, v34, v36
	ds_bpermute_b32 v34, v126, v35
	v_sub_f32_e32 v33, v33, v37
	v_mul_f32_e32 v33, 0x3fb8aa3b, v33
	v_exp_f32_e32 v33, v33
	s_waitcnt lgkmcnt(0)
	v_max_f32_e32 v34, v34, v34
	v_max_f32_e32 v34, v35, v34
	ds_bpermute_b32 v35, v127, v34
	s_waitcnt lgkmcnt(0)
	v_max_f32_e32 v35, v35, v35
	v_max_f32_e32 v34, v34, v35
	ds_bpermute_b32 v35, v128, v34
	s_waitcnt lgkmcnt(0)
	v_max_f32_e32 v35, v35, v35
	v_max_f32_e32 v34, v34, v35
	ds_bpermute_b32 v35, v129, v34
	s_waitcnt lgkmcnt(0)
	v_max_f32_e32 v35, v35, v35
	v_max_f32_e32 v36, v34, v35
	v_sub_f32_e32 v34, v90, v39
	v_mul_f32_e32 v34, 0x3fb8aa3b, v34
	v_exp_f32_e32 v34, v34
	v_sub_f32_e32 v32, v32, v36
	v_mul_f32_e32 v32, 0x3fb8aa3b, v32
	v_exp_f32_e32 v32, v32
	v_add_f32_e32 v35, 0, v34
	v_cvt_pk_bf16_f32 v34, v34, v169
	ds_write_b16 v130, v34
	v_sub_f32_e32 v34, v91, v38
	v_mul_f32_e32 v34, 0x3fb8aa3b, v34
	v_exp_f32_e32 v34, v34
	s_nop 0
	v_add_f32_e32 v90, 0, v34
	v_cvt_pk_bf16_f32 v34, v34, v169
	ds_write_b16 v130, v34 offset:528
	v_sub_f32_e32 v34, v92, v37
	v_mul_f32_e32 v34, 0x3fb8aa3b, v34
	v_exp_f32_e32 v34, v34
	s_nop 0
	v_add_f32_e32 v91, 0, v34
	v_cvt_pk_bf16_f32 v34, v34, v169
	ds_write_b16 v130, v34 offset:1056
	v_sub_f32_e32 v34, v94, v36
	v_mul_f32_e32 v34, 0x3fb8aa3b, v34
	v_exp_f32_e32 v34, v34
	s_nop 0
	v_add_f32_e32 v92, 0, v34
	v_cvt_pk_bf16_f32 v34, v34, v169
	ds_write_b16 v130, v34 offset:1584
	v_sub_f32_e32 v34, v88, v39
	v_mul_f32_e32 v34, 0x3fb8aa3b, v34
	v_exp_f32_e32 v34, v34
	s_nop 0
	v_add_f32_e32 v35, v34, v35
	v_cvt_pk_bf16_f32 v34, v34, v169
	ds_write_b16 v130, v34 offset:32
	v_sub_f32_e32 v34, v89, v38
	v_mul_f32_e32 v34, 0x3fb8aa3b, v34
	v_exp_f32_e32 v34, v34
	s_nop 0
	v_add_f32_e32 v88, v34, v90
	v_cvt_pk_bf16_f32 v34, v34, v169
	ds_write_b16 v130, v34 offset:560
	v_sub_f32_e32 v34, v93, v37
	v_mul_f32_e32 v34, 0x3fb8aa3b, v34
	v_exp_f32_e32 v34, v34
	s_nop 0
	v_add_f32_e32 v89, v34, v91
	v_cvt_pk_bf16_f32 v34, v34, v169
	ds_write_b16 v130, v34 offset:1088
	v_sub_f32_e32 v34, v95, v36
	v_mul_f32_e32 v34, 0x3fb8aa3b, v34
	v_exp_f32_e32 v34, v34
	s_nop 0
	v_add_f32_e32 v90, v34, v92
	v_cvt_pk_bf16_f32 v34, v34, v169
	ds_write_b16 v130, v34 offset:1616
	v_sub_f32_e32 v34, v84, v39
	v_mul_f32_e32 v34, 0x3fb8aa3b, v34
	v_exp_f32_e32 v34, v34
	s_nop 0
	v_add_f32_e32 v35, v34, v35
	v_cvt_pk_bf16_f32 v34, v34, v169
	ds_write_b16 v130, v34 offset:64
	v_sub_f32_e32 v34, v85, v38
	v_mul_f32_e32 v34, 0x3fb8aa3b, v34
	v_exp_f32_e32 v34, v34
	s_nop 0
	v_add_f32_e32 v84, v34, v88
	v_cvt_pk_bf16_f32 v34, v34, v169
	ds_write_b16 v130, v34 offset:592
	v_sub_f32_e32 v34, v86, v37
	v_mul_f32_e32 v34, 0x3fb8aa3b, v34
	v_exp_f32_e32 v34, v34
	s_nop 0
	v_add_f32_e32 v85, v34, v89
	v_cvt_pk_bf16_f32 v34, v34, v169
	ds_write_b16 v130, v34 offset:1120
	v_sub_f32_e32 v34, v87, v36
	v_mul_f32_e32 v34, 0x3fb8aa3b, v34
	v_exp_f32_e32 v34, v34
	s_nop 0
	v_add_f32_e32 v86, v34, v90
	v_cvt_pk_bf16_f32 v34, v34, v169
	ds_write_b16 v130, v34 offset:1648
	v_sub_f32_e32 v34, v80, v39
	v_mul_f32_e32 v34, 0x3fb8aa3b, v34
	v_exp_f32_e32 v34, v34
	s_nop 0
	v_add_f32_e32 v35, v34, v35
	v_cvt_pk_bf16_f32 v34, v34, v169
	ds_write_b16 v130, v34 offset:96
	v_sub_f32_e32 v34, v81, v38
	v_mul_f32_e32 v34, 0x3fb8aa3b, v34
	v_exp_f32_e32 v34, v34
	s_nop 0
	v_add_f32_e32 v80, v34, v84
	v_cvt_pk_bf16_f32 v34, v34, v169
	ds_write_b16 v130, v34 offset:624
	v_sub_f32_e32 v34, v82, v37
	v_mul_f32_e32 v34, 0x3fb8aa3b, v34
	v_exp_f32_e32 v34, v34
	s_nop 0
	v_add_f32_e32 v81, v34, v85
	v_cvt_pk_bf16_f32 v34, v34, v169
	ds_write_b16 v130, v34 offset:1152
	v_sub_f32_e32 v34, v83, v36
	v_mul_f32_e32 v34, 0x3fb8aa3b, v34
	v_exp_f32_e32 v34, v34
	s_nop 0
	v_add_f32_e32 v82, v34, v86
	v_cvt_pk_bf16_f32 v34, v34, v169
	ds_write_b16 v130, v34 offset:1680
	v_sub_f32_e32 v34, v76, v39
	v_mul_f32_e32 v34, 0x3fb8aa3b, v34
	v_exp_f32_e32 v34, v34
	s_nop 0
	v_add_f32_e32 v35, v34, v35
; __device__ __forceinline__ bf16_t f2bf(float f) { return (bf16_t)(cvt_pk_bf16(f, 0.f) & 0xffffu); }
; __device__ __forceinline__ void attn_phase(const Params& p, LAS unsigned char* lds) {
;     ...
;         for (int kb = 0; kb < 16; ++kb)
; #pragma unroll
;             for (int j = 0; j < 4; ++j) {
;                 const float pv = __expf(sa[kb][j] - mx[j]);
;                 ls[j] += pv;
;                 PLw[(fq * 4 + j) * 264 + kb * 16 + fr] = f2bf(pv);
;             }
	v_cvt_pk_bf16_f32 v34, v34, v169
	ds_write_b16 v130, v34 offset:128
	v_sub_f32_e32 v34, v77, v38
	v_mul_f32_e32 v34, 0x3fb8aa3b, v34
	v_exp_f32_e32 v34, v34
	s_nop 0
	v_add_f32_e32 v76, v34, v80
	v_cvt_pk_bf16_f32 v34, v34, v169
	ds_write_b16 v130, v34 offset:656
	v_sub_f32_e32 v34, v78, v37
	v_mul_f32_e32 v34, 0x3fb8aa3b, v34
	v_exp_f32_e32 v34, v34
	s_nop 0
	v_add_f32_e32 v77, v34, v81
	v_cvt_pk_bf16_f32 v34, v34, v169
	ds_write_b16 v130, v34 offset:1184
	v_sub_f32_e32 v34, v79, v36
	v_mul_f32_e32 v34, 0x3fb8aa3b, v34
	v_exp_f32_e32 v34, v34
	s_nop 0
	v_add_f32_e32 v78, v34, v82
	v_cvt_pk_bf16_f32 v34, v34, v169
	ds_write_b16 v130, v34 offset:1712
	v_sub_f32_e32 v34, v72, v39
	v_mul_f32_e32 v34, 0x3fb8aa3b, v34
	v_exp_f32_e32 v34, v34
	s_nop 0
	v_add_f32_e32 v35, v34, v35
	v_cvt_pk_bf16_f32 v34, v34, v169
	ds_write_b16 v130, v34 offset:160
	v_sub_f32_e32 v34, v73, v38
	v_mul_f32_e32 v34, 0x3fb8aa3b, v34
	v_exp_f32_e32 v34, v34
	s_nop 0
	v_add_f32_e32 v72, v34, v76
	v_cvt_pk_bf16_f32 v34, v34, v169
	ds_write_b16 v130, v34 offset:688
	v_sub_f32_e32 v34, v74, v37
	v_mul_f32_e32 v34, 0x3fb8aa3b, v34
	v_exp_f32_e32 v34, v34
	s_nop 0
	v_add_f32_e32 v73, v34, v77
	v_cvt_pk_bf16_f32 v34, v34, v169
	ds_write_b16 v130, v34 offset:1216
	v_sub_f32_e32 v34, v75, v36
	v_mul_f32_e32 v34, 0x3fb8aa3b, v34
	v_exp_f32_e32 v34, v34
	s_nop 0
	v_add_f32_e32 v74, v34, v78
	v_cvt_pk_bf16_f32 v34, v34, v169
	ds_write_b16 v130, v34 offset:1744
	v_sub_f32_e32 v34, v68, v39
	v_mul_f32_e32 v34, 0x3fb8aa3b, v34
	v_exp_f32_e32 v34, v34
	s_nop 0
	v_add_f32_e32 v35, v34, v35
	v_cvt_pk_bf16_f32 v34, v34, v169
	ds_write_b16 v130, v34 offset:192
	v_sub_f32_e32 v34, v69, v38
	v_mul_f32_e32 v34, 0x3fb8aa3b, v34
	v_exp_f32_e32 v34, v34
	s_nop 0
	v_add_f32_e32 v68, v34, v72
	v_cvt_pk_bf16_f32 v34, v34, v169
	ds_write_b16 v130, v34 offset:720
	v_sub_f32_e32 v34, v70, v37
	v_mul_f32_e32 v34, 0x3fb8aa3b, v34
	v_exp_f32_e32 v34, v34
	s_nop 0
	v_add_f32_e32 v69, v34, v73
	v_cvt_pk_bf16_f32 v34, v34, v169
	ds_write_b16 v130, v34 offset:1248
	v_sub_f32_e32 v34, v71, v36
	v_mul_f32_e32 v34, 0x3fb8aa3b, v34
	v_exp_f32_e32 v34, v34
	s_nop 0
	v_add_f32_e32 v70, v34, v74
	v_cvt_pk_bf16_f32 v34, v34, v169
	ds_write_b16 v130, v34 offset:1776
	v_sub_f32_e32 v34, v64, v39
	v_mul_f32_e32 v34, 0x3fb8aa3b, v34
	v_exp_f32_e32 v34, v34
	s_nop 0
	v_add_f32_e32 v35, v34, v35
	v_cvt_pk_bf16_f32 v34, v34, v169
	ds_write_b16 v130, v34 offset:224
	v_sub_f32_e32 v34, v65, v38
	v_mul_f32_e32 v34, 0x3fb8aa3b, v34
	v_exp_f32_e32 v34, v34
	s_nop 0
	v_add_f32_e32 v64, v34, v68
	v_cvt_pk_bf16_f32 v34, v34, v169
	ds_write_b16 v130, v34 offset:752
	v_sub_f32_e32 v34, v66, v37
	v_mul_f32_e32 v34, 0x3fb8aa3b, v34
	v_exp_f32_e32 v34, v34
	s_nop 0
	v_add_f32_e32 v65, v34, v69
	v_cvt_pk_bf16_f32 v34, v34, v169
	ds_write_b16 v130, v34 offset:1280
	v_sub_f32_e32 v34, v67, v36
	v_mul_f32_e32 v34, 0x3fb8aa3b, v34
	v_exp_f32_e32 v34, v34
	s_nop 0
	v_add_f32_e32 v66, v34, v70
	v_cvt_pk_bf16_f32 v34, v34, v169
	ds_write_b16 v130, v34 offset:1808
	v_sub_f32_e32 v34, v101, v39
	v_mul_f32_e32 v34, 0x3fb8aa3b, v34
	v_exp_f32_e32 v34, v34
	s_nop 0
	v_add_f32_e32 v35, v34, v35
	v_cvt_pk_bf16_f32 v34, v34, v169
	ds_write_b16 v130, v34 offset:256
	v_sub_f32_e32 v34, v100, v38
	v_mul_f32_e32 v34, 0x3fb8aa3b, v34
	v_exp_f32_e32 v34, v34
	s_nop 0
	v_add_f32_e32 v64, v34, v64
	v_cvt_pk_bf16_f32 v34, v34, v169
	ds_write_b16 v130, v34 offset:784
	v_sub_f32_e32 v34, v99, v37
	v_mul_f32_e32 v34, 0x3fb8aa3b, v34
	v_exp_f32_e32 v34, v34
	s_nop 0
	v_add_f32_e32 v65, v34, v65
	v_cvt_pk_bf16_f32 v34, v34, v169
	ds_write_b16 v130, v34 offset:1312
	v_sub_f32_e32 v34, v98, v36
	v_mul_f32_e32 v34, 0x3fb8aa3b, v34
	v_exp_f32_e32 v34, v34
	s_nop 0
	v_add_f32_e32 v66, v34, v66
	v_cvt_pk_bf16_f32 v34, v34, v169
	ds_write_b16 v130, v34 offset:1840
	v_sub_f32_e32 v34, v97, v39
	v_mul_f32_e32 v34, 0x3fb8aa3b, v34
	v_exp_f32_e32 v34, v34
	s_nop 0
	v_add_f32_e32 v35, v34, v35
	v_cvt_pk_bf16_f32 v34, v34, v169
	ds_write_b16 v130, v34 offset:288
	v_sub_f32_e32 v34, v96, v38
	v_mul_f32_e32 v34, 0x3fb8aa3b, v34
	v_exp_f32_e32 v34, v34
	s_nop 0
	v_add_f32_e32 v64, v34, v64
	v_cvt_pk_bf16_f32 v34, v34, v169
	ds_write_b16 v130, v34 offset:816
	v_sub_f32_e32 v34, v63, v37
	v_mul_f32_e32 v34, 0x3fb8aa3b, v34
	v_exp_f32_e32 v34, v34
	s_nop 0
	v_add_f32_e32 v63, v34, v65
	v_cvt_pk_bf16_f32 v34, v34, v169
	ds_write_b16 v130, v34 offset:1344
	v_sub_f32_e32 v34, v62, v36
	v_mul_f32_e32 v34, 0x3fb8aa3b, v34
	v_exp_f32_e32 v34, v34
	s_nop 0
	v_add_f32_e32 v62, v34, v66
	v_cvt_pk_bf16_f32 v34, v34, v169
	ds_write_b16 v130, v34 offset:1872
	v_sub_f32_e32 v34, v61, v39
	v_mul_f32_e32 v34, 0x3fb8aa3b, v34
	v_exp_f32_e32 v34, v34
	s_nop 0
	v_add_f32_e32 v35, v34, v35
	v_cvt_pk_bf16_f32 v34, v34, v169
	ds_write_b16 v130, v34 offset:320
	v_sub_f32_e32 v34, v60, v38
	v_mul_f32_e32 v34, 0x3fb8aa3b, v34
	v_exp_f32_e32 v34, v34
	s_nop 0
	v_add_f32_e32 v60, v34, v64
	v_cvt_pk_bf16_f32 v34, v34, v169
	ds_write_b16 v130, v34 offset:848
	v_sub_f32_e32 v34, v59, v37
	v_mul_f32_e32 v34, 0x3fb8aa3b, v34
	v_exp_f32_e32 v34, v34
	s_nop 0
	v_add_f32_e32 v59, v34, v63
	v_cvt_pk_bf16_f32 v34, v34, v169
	ds_write_b16 v130, v34 offset:1376
	v_sub_f32_e32 v34, v58, v36
	v_mul_f32_e32 v34, 0x3fb8aa3b, v34
	v_exp_f32_e32 v34, v34
	s_nop 0
	v_add_f32_e32 v58, v34, v62
	v_cvt_pk_bf16_f32 v34, v34, v169
	ds_write_b16 v130, v34 offset:1904
	v_sub_f32_e32 v34, v57, v39
	v_mul_f32_e32 v34, 0x3fb8aa3b, v34
	v_exp_f32_e32 v34, v34
	s_nop 0
	v_add_f32_e32 v35, v34, v35
	v_cvt_pk_bf16_f32 v34, v34, v169
	ds_write_b16 v130, v34 offset:352
	v_sub_f32_e32 v34, v56, v38
	v_mul_f32_e32 v34, 0x3fb8aa3b, v34
; #define LAS __attribute__((address_space(3)))
; __device__ __forceinline__ bf16_t f2bf(float f) { return (bf16_t)(cvt_pk_bf16(f, 0.f) & 0xffffu); }
; __device__ __forceinline__ void attn_phase(const Params& p, LAS unsigned char* lds) {
;     ...
;         for (int kb = 0; kb < 16; ++kb)
; #pragma unroll
;             for (int j = 0; j < 4; ++j) {
;                 const float pv = __expf(sa[kb][j] - mx[j]);
;                 ls[j] += pv;
;                 PLw[(fq * 4 + j) * 264 + kb * 16 + fr] = f2bf(pv);
;             }
; #pragma unroll
;         for (int j = 0; j < 4; ++j) {
; #pragma unroll
;             for (int o = 1; o < 16; o <<= 1) ls[j] += __shfl_xor(ls[j], o);
;         }
;         __syncthreads();
; #pragma unroll
;         for (int di = 0; di < 8; ++di) *(LAS u32x4*)(VtL + (db * 8 + di) * 264 + keyb * 8) = tr_col(vin, di);
;         __syncthreads();
	v_exp_f32_e32 v34, v34
	s_nop 0
	v_add_f32_e32 v56, v34, v60
	v_cvt_pk_bf16_f32 v34, v34, v169
	ds_write_b16 v130, v34 offset:880
	v_sub_f32_e32 v34, v55, v37
	v_mul_f32_e32 v34, 0x3fb8aa3b, v34
	v_exp_f32_e32 v34, v34
	s_nop 0
	v_add_f32_e32 v55, v34, v59
	v_cvt_pk_bf16_f32 v34, v34, v169
	ds_write_b16 v130, v34 offset:1408
	v_sub_f32_e32 v34, v54, v36
	v_mul_f32_e32 v34, 0x3fb8aa3b, v34
	v_exp_f32_e32 v34, v34
	s_nop 0
	v_add_f32_e32 v54, v34, v58
	v_cvt_pk_bf16_f32 v34, v34, v169
	ds_write_b16 v130, v34 offset:1936
	v_sub_f32_e32 v34, v53, v39
	v_mul_f32_e32 v34, 0x3fb8aa3b, v34
	v_exp_f32_e32 v34, v34
	s_nop 0
	v_add_f32_e32 v35, v34, v35
	v_cvt_pk_bf16_f32 v34, v34, v169
	ds_write_b16 v130, v34 offset:384
	v_sub_f32_e32 v34, v52, v38
	v_mul_f32_e32 v34, 0x3fb8aa3b, v34
	v_exp_f32_e32 v34, v34
	s_nop 0
	v_add_f32_e32 v52, v34, v56
	v_cvt_pk_bf16_f32 v34, v34, v169
	ds_write_b16 v130, v34 offset:912
	v_sub_f32_e32 v34, v51, v37
	v_mul_f32_e32 v34, 0x3fb8aa3b, v34
	v_exp_f32_e32 v34, v34
	s_nop 0
	v_add_f32_e32 v51, v34, v55
	v_cvt_pk_bf16_f32 v34, v34, v169
	ds_write_b16 v130, v34 offset:1440
	v_sub_f32_e32 v34, v50, v36
	v_mul_f32_e32 v34, 0x3fb8aa3b, v34
	v_exp_f32_e32 v34, v34
	s_nop 0
	v_add_f32_e32 v50, v34, v54
	v_cvt_pk_bf16_f32 v34, v34, v169
	ds_write_b16 v130, v34 offset:1968
	v_sub_f32_e32 v34, v49, v39
	v_mul_f32_e32 v34, 0x3fb8aa3b, v34
	v_exp_f32_e32 v34, v34
	s_nop 0
	v_add_f32_e32 v35, v34, v35
	v_cvt_pk_bf16_f32 v34, v34, v169
	ds_write_b16 v130, v34 offset:416
	v_sub_f32_e32 v34, v48, v38
	v_mul_f32_e32 v34, 0x3fb8aa3b, v34
	v_exp_f32_e32 v34, v34
	s_nop 0
	v_add_f32_e32 v48, v34, v52
	v_cvt_pk_bf16_f32 v34, v34, v169
	ds_write_b16 v130, v34 offset:944
	v_sub_f32_e32 v34, v47, v37
	v_mul_f32_e32 v34, 0x3fb8aa3b, v34
	v_exp_f32_e32 v34, v34
	s_nop 0
	v_add_f32_e32 v47, v34, v51
	v_cvt_pk_bf16_f32 v34, v34, v169
	ds_write_b16 v130, v34 offset:1472
	v_sub_f32_e32 v34, v46, v36
	v_mul_f32_e32 v34, 0x3fb8aa3b, v34
	v_exp_f32_e32 v34, v34
	s_nop 0
	v_add_f32_e32 v46, v34, v50
	v_cvt_pk_bf16_f32 v34, v34, v169
	ds_write_b16 v130, v34 offset:2000
	v_sub_f32_e32 v34, v45, v39
	v_mul_f32_e32 v34, 0x3fb8aa3b, v34
	v_exp_f32_e32 v34, v34
	s_nop 0
	v_add_f32_e32 v35, v34, v35
	v_cvt_pk_bf16_f32 v34, v34, v169
	ds_write_b16 v130, v34 offset:448
	v_sub_f32_e32 v34, v44, v38
	v_mul_f32_e32 v34, 0x3fb8aa3b, v34
	v_exp_f32_e32 v34, v34
	s_nop 0
	v_add_f32_e32 v44, v34, v48
	v_cvt_pk_bf16_f32 v34, v34, v169
	ds_write_b16 v130, v34 offset:976
	v_sub_f32_e32 v34, v43, v37
	v_mul_f32_e32 v34, 0x3fb8aa3b, v34
	v_exp_f32_e32 v34, v34
	s_nop 0
	v_add_f32_e32 v43, v34, v47
	v_cvt_pk_bf16_f32 v34, v34, v169
	ds_write_b16 v130, v34 offset:1504
	v_sub_f32_e32 v34, v42, v36
	v_mul_f32_e32 v34, 0x3fb8aa3b, v34
	v_exp_f32_e32 v34, v34
	v_add_u32_e32 v47, v114, v116
	v_add_f32_e32 v42, v34, v46
	v_cvt_pk_bf16_f32 v34, v34, v169
	ds_write_b16 v130, v34 offset:2032
	v_sub_f32_e32 v34, v41, v39
	v_mul_f32_e32 v34, 0x3fb8aa3b, v34
	v_exp_f32_e32 v34, v34
	s_nop 0
	v_add_f32_e32 v35, v34, v35
	v_cvt_pk_bf16_f32 v34, v34, v169
	ds_write_b16 v130, v34 offset:480
	v_sub_f32_e32 v34, v40, v38
	v_mul_f32_e32 v34, 0x3fb8aa3b, v34
	v_exp_f32_e32 v34, v34
	s_nop 0
	v_add_f32_e32 v40, v34, v44
	v_cvt_pk_bf16_f32 v34, v34, v169
	ds_write_b16 v130, v34 offset:1008
	v_add_f32_e32 v34, v33, v43
	v_cvt_pk_bf16_f32 v33, v33, v169
	ds_write_b16 v130, v33 offset:1536
	v_add_f32_e32 v33, v32, v42
	v_cvt_pk_bf16_f32 v32, v32, v169
	ds_write_b16 v130, v32 offset:2064
	ds_bpermute_b32 v32, v126, v35
	s_waitcnt lgkmcnt(0)
	s_barrier
	v_add_f32_e32 v32, v35, v32
	ds_bpermute_b32 v35, v127, v32
	s_waitcnt lgkmcnt(0)
	v_add_f32_e32 v32, v32, v35
	ds_bpermute_b32 v35, v128, v32
	s_waitcnt lgkmcnt(0)
	v_add_f32_e32 v32, v32, v35
	ds_bpermute_b32 v35, v129, v32
	s_waitcnt lgkmcnt(0)
	v_add_f32_e32 v46, v32, v35
	ds_bpermute_b32 v32, v126, v40
	s_waitcnt lgkmcnt(0)
	v_add_f32_e32 v32, v40, v32
	ds_bpermute_b32 v35, v127, v32
	s_waitcnt lgkmcnt(0)
	v_add_f32_e32 v32, v32, v35
	ds_bpermute_b32 v35, v128, v32
	s_waitcnt lgkmcnt(0)
	v_add_f32_e32 v44, v32, v35
	ds_bpermute_b32 v32, v126, v34
	s_waitcnt vmcnt(0)
	v_and_b32_e32 v35, 0xffff, v28
	v_lshl_or_b32 v35, v24, 16, v35
	ds_bpermute_b32 v45, v129, v44
	s_waitcnt lgkmcnt(1)
	v_add_f32_e32 v32, v34, v32
	ds_bpermute_b32 v34, v127, v32
	s_waitcnt lgkmcnt(0)
	v_add_f32_e32 v32, v32, v34
	ds_bpermute_b32 v34, v128, v32
	s_waitcnt lgkmcnt(0)
	v_add_f32_e32 v42, v32, v34
	ds_bpermute_b32 v32, v126, v33
	v_and_b32_e32 v34, 0xffff, v20
	v_lshl_or_b32 v34, v16, 16, v34
	ds_bpermute_b32 v43, v129, v42
	s_waitcnt lgkmcnt(1)
	v_add_f32_e32 v32, v33, v32
	ds_bpermute_b32 v33, v127, v32
	s_waitcnt lgkmcnt(0)
	v_add_f32_e32 v32, v32, v33
	ds_bpermute_b32 v33, v128, v32
	s_waitcnt lgkmcnt(0)
	v_add_f32_e32 v40, v32, v33
	v_and_b32_e32 v32, 0xffff, v4
	v_and_b32_e32 v33, 0xffff, v12
	v_lshl_or_b32 v32, v0, 16, v32
	v_lshl_or_b32 v33, v8, 16, v33
	v_lshrrev_b32_e32 v4, 16, v4
	ds_write_b128 v140, v[32:35]
	v_and_or_b32 v32, v0, s85, v4
	v_lshrrev_b32_e32 v0, 16, v12
	v_and_or_b32 v33, v8, s85, v0
	v_lshrrev_b32_e32 v0, 16, v20
	v_and_or_b32 v34, v16, s85, v0
	v_lshrrev_b32_e32 v0, 16, v28
	v_and_or_b32 v35, v24, s85, v0
	v_and_b32_e32 v0, 0xffff, v5
	ds_write_b128 v140, v[32:35] offset:528
	v_lshl_or_b32 v32, v1, 16, v0
	v_and_b32_e32 v0, 0xffff, v13
	v_lshl_or_b32 v33, v9, 16, v0
	v_and_b32_e32 v0, 0xffff, v21
	v_lshl_or_b32 v34, v17, 16, v0
	v_and_b32_e32 v0, 0xffff, v29
	v_lshl_or_b32 v35, v25, 16, v0
	v_lshrrev_b32_e32 v0, 16, v5
	ds_write_b128 v140, v[32:35] offset:1056
	v_and_or_b32 v32, v1, s85, v0
	v_lshrrev_b32_e32 v0, 16, v13
	v_and_or_b32 v33, v9, s85, v0
	v_lshrrev_b32_e32 v0, 16, v21
	v_and_or_b32 v34, v17, s85, v0
	v_lshrrev_b32_e32 v0, 16, v29
	v_and_or_b32 v35, v25, s85, v0
	v_and_b32_e32 v0, 0xffff, v6
	ds_write_b128 v140, v[32:35] offset:1584
	v_lshl_or_b32 v32, v2, 16, v0
	v_and_b32_e32 v0, 0xffff, v14
	v_lshl_or_b32 v33, v10, 16, v0
	v_and_b32_e32 v0, 0xffff, v22
	v_lshl_or_b32 v34, v18, 16, v0
	v_and_b32_e32 v0, 0xffff, v30
	v_lshl_or_b32 v35, v26, 16, v0
	v_lshrrev_b32_e32 v0, 16, v6
	ds_write_b128 v140, v[32:35] offset:2112
	v_and_or_b32 v32, v2, s85, v0
	v_lshrrev_b32_e32 v0, 16, v14
	v_and_or_b32 v33, v10, s85, v0
	v_lshrrev_b32_e32 v0, 16, v22
	v_and_or_b32 v34, v18, s85, v0
	v_lshrrev_b32_e32 v0, 16, v30
	v_and_or_b32 v35, v26, s85, v0
	v_and_b32_e32 v0, 0xffff, v7
	ds_write_b128 v140, v[32:35] offset:2640
	v_lshl_or_b32 v32, v3, 16, v0
	v_and_b32_e32 v0, 0xffff, v15
	v_lshl_or_b32 v33, v11, 16, v0
	v_and_b32_e32 v0, 0xffff, v23
	v_lshl_or_b32 v34, v19, 16, v0
	v_and_b32_e32 v0, 0xffff, v31
	v_lshl_or_b32 v35, v27, 16, v0
	v_lshrrev_b32_e32 v0, 16, v7
	v_and_or_b32 v0, v3, s85, v0
	v_lshrrev_b32_e32 v1, 16, v15
	v_lshrrev_b32_e32 v2, 16, v23
	v_lshrrev_b32_e32 v3, 16, v31
	v_and_or_b32 v1, v11, s85, v1
	v_and_or_b32 v2, v19, s85, v2
	v_and_or_b32 v3, v27, s85, v3
	ds_write_b128 v140, v[32:35] offset:3168
	ds_write_b128 v140, v[0:3] offset:3696
	s_waitcnt lgkmcnt(0)
	s_barrier
; #define LAS __attribute__((address_space(3)))
; __device__ __forceinline__ void attn_phase(const Params& p, LAS unsigned char* lds) {
;     ...
;         f32x4 oa[8];
; #pragma unroll
;         for (int nb = 0; nb < 8; ++nb) oa[nb] = (f32x4){0.f, 0.f, 0.f, 0.f};
; #pragma unroll
;         for (int ks = 0; ks < 8; ++ks) {
;             const bf16x8 Pf = *(const LAS bf16x8*)(PLw + fr * 264 + ks * 32 + fq * 8);
; #pragma unroll
;             for (int nb = 0; nb < 8; ++nb) {
;                 const bf16x8 Vf = *(const LAS bf16x8*)(VtL + (nb * 16 + fr) * 264 + ks * 32 + fq * 8);
;                 oa[nb] = __builtin_amdgcn_mfma_f32_16x16x32_bf16(Pf, Vf, oa[nb], 0, 0, 0);
;             }
;         }
	ds_read_b128 v[0:3], v117
	ds_read_b128 v[4:7], v47
	ds_read_b128 v[8:11], v141
	ds_read_b128 v[32:35], v141 offset:50688
	ds_read_b128 v[12:15], v141 offset:8448
	ds_read_b128 v[16:19], v141 offset:16896
	ds_read_b128 v[20:23], v141 offset:25344
	ds_read_b128 v[24:27], v141 offset:33792
	ds_read_b128 v[28:31], v141 offset:42240
	s_waitcnt lgkmcnt(7)
	v_mfma_f32_16x16x32_bf16 v[4:7], v[0:3], v[4:7], 0
	ds_bpermute_b32 v41, v129, v40
	s_waitcnt lgkmcnt(7)
	v_mfma_f32_16x16x32_bf16 v[8:11], v[0:3], v[8:11], 0
	s_waitcnt lgkmcnt(5)
	v_mfma_f32_16x16x32_bf16 v[12:15], v[0:3], v[12:15], 0
	s_waitcnt lgkmcnt(4)
	v_mfma_f32_16x16x32_bf16 v[16:19], v[0:3], v[16:19], 0
	s_waitcnt lgkmcnt(3)
	v_mfma_f32_16x16x32_bf16 v[20:23], v[0:3], v[20:23], 0
	s_waitcnt lgkmcnt(2)
	v_mfma_f32_16x16x32_bf16 v[24:27], v[0:3], v[24:27], 0
	s_waitcnt lgkmcnt(1)
	v_mfma_f32_16x16x32_bf16 v[28:31], v[0:3], v[28:31], 0
	v_mfma_f32_16x16x32_bf16 v[0:3], v[0:3], v[32:35], 0
	ds_read_b128 v[32:35], v117 offset:64
	ds_read_b128 v[48:51], v47 offset:64
	s_waitcnt lgkmcnt(0)
	v_mfma_f32_16x16x32_bf16 v[4:7], v[32:35], v[48:51], v[4:7]
	ds_read_b128 v[48:51], v141 offset:64
	s_waitcnt lgkmcnt(0)
	v_mfma_f32_16x16x32_bf16 v[8:11], v[32:35], v[48:51], v[8:11]
	ds_read_b128 v[48:51], v141 offset:8512
	s_waitcnt lgkmcnt(0)
	v_mfma_f32_16x16x32_bf16 v[12:15], v[32:35], v[48:51], v[12:15]
	ds_read_b128 v[48:51], v141 offset:16960
	s_waitcnt lgkmcnt(0)
	v_mfma_f32_16x16x32_bf16 v[16:19], v[32:35], v[48:51], v[16:19]
	ds_read_b128 v[48:51], v141 offset:25408
	s_waitcnt lgkmcnt(0)
	v_mfma_f32_16x16x32_bf16 v[20:23], v[32:35], v[48:51], v[20:23]
	ds_read_b128 v[48:51], v141 offset:33856
	s_waitcnt lgkmcnt(0)
	v_mfma_f32_16x16x32_bf16 v[24:27], v[32:35], v[48:51], v[24:27]
	ds_read_b128 v[48:51], v141 offset:42304
	s_waitcnt lgkmcnt(0)
	v_mfma_f32_16x16x32_bf16 v[28:31], v[32:35], v[48:51], v[28:31]
	ds_read_b128 v[48:51], v141 offset:50752
	s_waitcnt lgkmcnt(0)
	v_mfma_f32_16x16x32_bf16 v[0:3], v[32:35], v[48:51], v[0:3]
	ds_read_b128 v[32:35], v117 offset:128
	ds_read_b128 v[48:51], v47 offset:128
	s_waitcnt lgkmcnt(0)
	v_mfma_f32_16x16x32_bf16 v[4:7], v[32:35], v[48:51], v[4:7]
	ds_read_b128 v[48:51], v141 offset:128
	s_waitcnt lgkmcnt(0)
	v_mfma_f32_16x16x32_bf16 v[8:11], v[32:35], v[48:51], v[8:11]
	ds_read_b128 v[48:51], v141 offset:8576
	s_waitcnt lgkmcnt(0)
	v_mfma_f32_16x16x32_bf16 v[12:15], v[32:35], v[48:51], v[12:15]
	ds_read_b128 v[48:51], v141 offset:17024
	s_waitcnt lgkmcnt(0)
	v_mfma_f32_16x16x32_bf16 v[16:19], v[32:35], v[48:51], v[16:19]
	ds_read_b128 v[48:51], v141 offset:25472
	s_waitcnt lgkmcnt(0)
	v_mfma_f32_16x16x32_bf16 v[20:23], v[32:35], v[48:51], v[20:23]
	ds_read_b128 v[48:51], v141 offset:33920
	s_waitcnt lgkmcnt(0)
	v_mfma_f32_16x16x32_bf16 v[24:27], v[32:35], v[48:51], v[24:27]
	ds_read_b128 v[48:51], v141 offset:42368
	s_waitcnt lgkmcnt(0)
	v_mfma_f32_16x16x32_bf16 v[28:31], v[32:35], v[48:51], v[28:31]
	ds_read_b128 v[48:51], v141 offset:50816
	s_waitcnt lgkmcnt(0)
	v_mfma_f32_16x16x32_bf16 v[0:3], v[32:35], v[48:51], v[0:3]
	ds_read_b128 v[32:35], v117 offset:192
	ds_read_b128 v[48:51], v47 offset:192
	s_waitcnt lgkmcnt(0)
	v_mfma_f32_16x16x32_bf16 v[4:7], v[32:35], v[48:51], v[4:7]
	ds_read_b128 v[48:51], v141 offset:192
	s_waitcnt lgkmcnt(0)
	v_mfma_f32_16x16x32_bf16 v[8:11], v[32:35], v[48:51], v[8:11]
	ds_read_b128 v[48:51], v141 offset:8640
	s_waitcnt lgkmcnt(0)
	v_mfma_f32_16x16x32_bf16 v[12:15], v[32:35], v[48:51], v[12:15]
	ds_read_b128 v[48:51], v141 offset:17088
	s_waitcnt lgkmcnt(0)
	v_mfma_f32_16x16x32_bf16 v[16:19], v[32:35], v[48:51], v[16:19]
	ds_read_b128 v[48:51], v141 offset:25536
	s_waitcnt lgkmcnt(0)
	v_mfma_f32_16x16x32_bf16 v[20:23], v[32:35], v[48:51], v[20:23]
	ds_read_b128 v[48:51], v141 offset:33984
	s_waitcnt lgkmcnt(0)
	v_mfma_f32_16x16x32_bf16 v[24:27], v[32:35], v[48:51], v[24:27]
	ds_read_b128 v[48:51], v141 offset:42432
	s_waitcnt lgkmcnt(0)
	v_mfma_f32_16x16x32_bf16 v[28:31], v[32:35], v[48:51], v[28:31]
	ds_read_b128 v[48:51], v141 offset:50880
	s_waitcnt lgkmcnt(0)
	v_mfma_f32_16x16x32_bf16 v[0:3], v[32:35], v[48:51], v[0:3]
	ds_read_b128 v[32:35], v117 offset:256
	ds_read_b128 v[48:51], v47 offset:256
	s_waitcnt lgkmcnt(0)
	v_mfma_f32_16x16x32_bf16 v[4:7], v[32:35], v[48:51], v[4:7]
	ds_read_b128 v[48:51], v141 offset:256
	s_waitcnt lgkmcnt(0)
	v_mfma_f32_16x16x32_bf16 v[8:11], v[32:35], v[48:51], v[8:11]
	ds_read_b128 v[48:51], v141 offset:8704
	s_waitcnt lgkmcnt(0)
	v_mfma_f32_16x16x32_bf16 v[12:15], v[32:35], v[48:51], v[12:15]
	ds_read_b128 v[48:51], v141 offset:17152
	s_waitcnt lgkmcnt(0)
	v_mfma_f32_16x16x32_bf16 v[16:19], v[32:35], v[48:51], v[16:19]
	ds_read_b128 v[48:51], v141 offset:25600
	s_waitcnt lgkmcnt(0)
	v_mfma_f32_16x16x32_bf16 v[20:23], v[32:35], v[48:51], v[20:23]
	ds_read_b128 v[48:51], v141 offset:34048
	s_waitcnt lgkmcnt(0)
	v_mfma_f32_16x16x32_bf16 v[24:27], v[32:35], v[48:51], v[24:27]
	ds_read_b128 v[48:51], v141 offset:42496
	s_waitcnt lgkmcnt(0)
	v_mfma_f32_16x16x32_bf16 v[28:31], v[32:35], v[48:51], v[28:31]
	ds_read_b128 v[48:51], v141 offset:50944
	s_waitcnt lgkmcnt(0)
	v_mfma_f32_16x16x32_bf16 v[0:3], v[32:35], v[48:51], v[0:3]
	ds_read_b128 v[32:35], v117 offset:320
	ds_read_b128 v[48:51], v47 offset:320
	s_waitcnt lgkmcnt(0)
; #define LAS __attribute__((address_space(3)))
; __device__ __forceinline__ bf16_t f2bf(float f) { return (bf16_t)(cvt_pk_bf16(f, 0.f) & 0xffffu); }
; __device__ __forceinline__ void attn_phase(const Params& p, LAS unsigned char* lds) {
;     ...
;         for (int ks = 0; ks < 8; ++ks) {
;             const bf16x8 Pf = *(const LAS bf16x8*)(PLw + fr * 264 + ks * 32 + fq * 8);
; #pragma unroll
;             for (int nb = 0; nb < 8; ++nb) {
;                 const bf16x8 Vf = *(const LAS bf16x8*)(VtL + (nb * 16 + fr) * 264 + ks * 32 + fq * 8);
;                 oa[nb] = __builtin_amdgcn_mfma_f32_16x16x32_bf16(Pf, Vf, oa[nb], 0, 0, 0);
;             }
;         }
; #pragma unroll
;         for (int j = 0; j < 4; ++j) {
;             const size_t tok = (size_t)(r + d * (i0 + wid * 16 + fq * 4 + j));
;             const float inv = 1.0f / ls[j];
;             bf16_t* orow = og + ((size_t)g * SEQ + tok) * 1024 + h * 128 + fr;
; #pragma unroll
;             for (int nb = 0; nb < 8; ++nb) orow[nb * 16] = f2bf(oa[nb][j] * inv);
;             if (fr == 0) lse[((size_t)g * SEQ + tok) * 8 + h] = mx[j] + logf(ls[j]);
	v_mfma_f32_16x16x32_bf16 v[4:7], v[32:35], v[48:51], v[4:7]
	ds_read_b128 v[48:51], v141 offset:320
	s_waitcnt lgkmcnt(0)
	v_mfma_f32_16x16x32_bf16 v[8:11], v[32:35], v[48:51], v[8:11]
	ds_read_b128 v[48:51], v141 offset:8768
	s_waitcnt lgkmcnt(0)
	v_mfma_f32_16x16x32_bf16 v[12:15], v[32:35], v[48:51], v[12:15]
	ds_read_b128 v[48:51], v141 offset:17216
	s_waitcnt lgkmcnt(0)
	v_mfma_f32_16x16x32_bf16 v[16:19], v[32:35], v[48:51], v[16:19]
	ds_read_b128 v[48:51], v141 offset:25664
	s_waitcnt lgkmcnt(0)
	v_mfma_f32_16x16x32_bf16 v[20:23], v[32:35], v[48:51], v[20:23]
	ds_read_b128 v[48:51], v141 offset:34112
	s_waitcnt lgkmcnt(0)
	v_mfma_f32_16x16x32_bf16 v[24:27], v[32:35], v[48:51], v[24:27]
	ds_read_b128 v[48:51], v141 offset:42560
	s_waitcnt lgkmcnt(0)
	v_mfma_f32_16x16x32_bf16 v[28:31], v[32:35], v[48:51], v[28:31]
	ds_read_b128 v[48:51], v141 offset:51008
	s_waitcnt lgkmcnt(0)
	v_mfma_f32_16x16x32_bf16 v[0:3], v[32:35], v[48:51], v[0:3]
	ds_read_b128 v[32:35], v117 offset:384
	ds_read_b128 v[48:51], v47 offset:384
	s_waitcnt lgkmcnt(0)
	v_mfma_f32_16x16x32_bf16 v[4:7], v[32:35], v[48:51], v[4:7]
	ds_read_b128 v[48:51], v141 offset:384
	s_waitcnt lgkmcnt(0)
	v_mfma_f32_16x16x32_bf16 v[8:11], v[32:35], v[48:51], v[8:11]
	ds_read_b128 v[48:51], v141 offset:8832
	s_waitcnt lgkmcnt(0)
	v_mfma_f32_16x16x32_bf16 v[12:15], v[32:35], v[48:51], v[12:15]
	ds_read_b128 v[48:51], v141 offset:17280
	s_waitcnt lgkmcnt(0)
	v_mfma_f32_16x16x32_bf16 v[16:19], v[32:35], v[48:51], v[16:19]
	ds_read_b128 v[48:51], v141 offset:25728
	s_waitcnt lgkmcnt(0)
	v_mfma_f32_16x16x32_bf16 v[48:51], v[32:35], v[48:51], v[20:23]
	s_nop 2
	ds_read_b128 v[20:23], v141 offset:34176
	s_waitcnt lgkmcnt(0)
	v_mfma_f32_16x16x32_bf16 v[52:55], v[32:35], v[20:23], v[24:27]
	ds_read_b128 v[20:23], v141 offset:42624
	s_waitcnt lgkmcnt(0)
	v_mfma_f32_16x16x32_bf16 v[56:59], v[32:35], v[20:23], v[28:31]
	ds_read_b128 v[20:23], v141 offset:51072
	s_waitcnt lgkmcnt(0)
	v_mfma_f32_16x16x32_bf16 v[0:3], v[32:35], v[20:23], v[0:3]
	ds_read_b128 v[32:35], v117 offset:448
	ds_read_b128 v[20:23], v47 offset:448
	v_or_b32_e32 v47, v142, v115
	s_waitcnt lgkmcnt(0)
	v_mfma_f32_16x16x32_bf16 v[28:31], v[32:35], v[20:23], v[4:7]
	s_nop 2
	ds_read_b128 v[4:7], v141 offset:448
	s_waitcnt lgkmcnt(0)
	v_mfma_f32_16x16x32_bf16 v[24:27], v[32:35], v[4:7], v[8:11]
	ds_read_b128 v[4:7], v141 offset:8896
	s_waitcnt lgkmcnt(0)
	v_mfma_f32_16x16x32_bf16 v[20:23], v[32:35], v[4:7], v[12:15]
	ds_read_b128 v[4:7], v141 offset:17344
	s_waitcnt lgkmcnt(0)
	v_mfma_f32_16x16x32_bf16 v[16:19], v[32:35], v[4:7], v[16:19]
	ds_read_b128 v[4:7], v141 offset:25792
	s_waitcnt lgkmcnt(0)
	v_mfma_f32_16x16x32_bf16 v[12:15], v[32:35], v[4:7], v[48:51]
	ds_read_b128 v[4:7], v141 offset:34240
	s_nop 1
	ds_read_b128 v[48:51], v141 offset:51136
	s_waitcnt lgkmcnt(0)
	v_mfma_f32_16x16x32_bf16 v[0:3], v[32:35], v[48:51], v[0:3]
	v_div_scale_f32 v48, s[78:79], v46, v46, 1.0
	v_rcp_f32_e32 v49, v48
	v_mfma_f32_16x16x32_bf16 v[8:11], v[32:35], v[4:7], v[52:55]
	ds_read_b128 v[4:7], v141 offset:42688
	v_fma_f32 v50, -v48, v49, 1.0
	v_fmac_f32_e32 v49, v50, v49
	v_div_scale_f32 v50, vcc, 1.0, v46, 1.0
	v_mul_f32_e32 v51, v50, v49
	s_waitcnt lgkmcnt(0)
	v_mfma_f32_16x16x32_bf16 v[4:7], v[32:35], v[4:7], v[56:59]
	v_lshlrev_b32_e32 v34, s47, v47
	v_fma_f32 v52, -v48, v51, v50
	v_add_u32_e32 v34, s50, v34
	v_fmac_f32_e32 v51, v52, v49
	v_ashrrev_i32_e32 v35, 31, v34
	v_fma_f32 v48, -v48, v51, v50
	v_lshl_add_u64 v[32:33], v[110:111], 0, s[2:3]
	s_lshl_b32 s2, s51, 2
	v_div_fmas_f32 v48, v48, v49, v51
	v_lshl_add_u64 v[34:35], s[76:77], 0, v[34:35]
	s_add_u32 s40, s95, s2
	v_readlane_b32 s2, v239, 42
	v_div_fixup_f32 v50, v48, v46, 1.0
	v_lshlrev_b64 v[48:49], 11, v[34:35]
	s_addc_u32 s41, s2, 0
	v_lshl_add_u64 v[48:49], v[32:33], 0, v[48:49]
	v_mul_f32_e32 v28, v50, v28
	v_mul_f32_e32 v24, v50, v24
	v_mul_f32_e32 v20, v50, v20
	v_mul_f32_e32 v16, v50, v16
	v_mul_f32_e32 v12, v50, v12
	v_mul_f32_e32 v8, v50, v8
	v_mul_f32_e32 v4, v50, v4
	v_mul_f32_e32 v0, v50, v0
	v_cvt_pk_bf16_f32 v28, v28, v169
	global_store_short v[48:49], v28, off
	v_cvt_pk_bf16_f32 v24, v24, v169
	global_store_short v[48:49], v24, off offset:32
	v_cvt_pk_bf16_f32 v20, v20, v169
	global_store_short v[48:49], v20, off offset:64
	v_cvt_pk_bf16_f32 v16, v16, v169
	global_store_short v[48:49], v16, off offset:96
	v_cvt_pk_bf16_f32 v12, v12, v169
	global_store_short v[48:49], v12, off offset:128
	v_cvt_pk_bf16_f32 v8, v8, v169
	global_store_short v[48:49], v8, off offset:160
	v_cvt_pk_bf16_f32 v4, v4, v169
	global_store_short v[48:49], v4, off offset:192
	v_cvt_pk_bf16_f32 v0, v0, v169
	global_store_short v[48:49], v0, off offset:224
	s_and_saveexec_b64 s[78:79], s[4:5]
	s_cbranch_execz .LBB0_212
	s_mov_b32 s2, 0x800000
	v_cmp_gt_f32_e32 vcc, s2, v46
	s_mov_b32 s2, 0x3f317217
	v_lshlrev_b64 v[34:35], 5, v[34:35]
	v_cndmask_b32_e64 v0, 0, 32, vcc
	v_ldexp_f32 v0, v46, v0
	v_log_f32_e32 v0, v0
	v_cndmask_b32_e32 v4, 0, v205, vcc
	v_lshl_add_u64 v[34:35], s[40:41], 0, v[34:35]
	v_mul_f32_e32 v8, 0x3f317217, v0
	v_fma_f32 v8, v0, s2, -v8
	v_fmac_f32_e32 v8, 0x3377d1cf, v0
	s_mov_b32 s2, 0x7f800000
	v_fmac_f32_e32 v8, 0x3f317217, v0
	v_cmp_lt_f32_e64 vcc, |v0|, s2
	s_nop 1
	v_cndmask_b32_e32 v0, v0, v8, vcc
	v_sub_f32_e32 v0, v0, v4
	v_add_f32_e32 v0, v39, v0
	global_store_dword v[34:35], v0, off
